# P2a tile loop: overflow flag raised with v_cmpx (no scalar round trip), thresholds kept in VGPRs across tiles
# baseline (speedup 1.0000x reference)
.LBB0_570:
	s_mov_b32 s5, s17
	s_add_i32 s17, s17, -1
	s_mov_b32 s29, s0
	s_mul_i32 s0, s5, s17
	s_lshr_b32 s1, s0, 31
	s_add_i32 s0, s0, s1
	s_ashr_i32 s59, s0, 1
	s_add_i32 s0, s29, -1
	s_cmp_lt_i32 s2, s59
	s_cbranch_scc1 .LBB0_570
	s_and_b64 s[0:1], s[10:11], exec
	s_cselect_b32 s6, 0x2000, 0
	s_lshl_b32 s3, s17, 6
	s_add_i32 s7, s3, s6
	v_add_u32_e32 v2, s7, v173
	v_mad_i64_i32 v[0:1], s[0:1], v2, s4, v[120:121]
	global_load_dwordx4 v[72:75], v[0:1], off offset:3072
	global_load_dwordx4 v[76:79], v[0:1], off offset:3104
	global_load_dwordx4 v[80:83], v[0:1], off offset:3136
	global_load_dwordx4 v[84:87], v[0:1], off offset:3168
	v_or_b32_e32 v0, 4, v2
	v_mad_i64_i32 v[0:1], s[0:1], v0, s4, v[120:121]
	global_load_dwordx4 v[88:91], v[0:1], off offset:3072
	global_load_dwordx4 v[92:95], v[0:1], off offset:3104
	global_load_dwordx4 v[96:99], v[0:1], off offset:3136
	global_load_dwordx4 v[100:103], v[0:1], off offset:3168
	v_add_u32_e32 v0, s7, v174
	v_ashrrev_i32_e32 v1, 31, v0
	v_lshlrev_b64 v[0:1], 5, v[0:1]
	v_lshl_add_u64 v[0:1], s[54:55], 0, v[0:1]
	global_load_dwordx4 v[28:31], v[0:1], off
	global_load_dwordx4 v[12:15], v[0:1], off offset:16
	v_add_u32_e32 v0, s7, v175
	v_ashrrev_i32_e32 v1, 31, v0
	v_lshlrev_b64 v[0:1], 5, v[0:1]
	v_lshl_add_u64 v[0:1], s[54:55], 0, v[0:1]
	global_load_dwordx4 v[24:27], v[0:1], off
	global_load_dwordx4 v[8:11], v[0:1], off offset:16
	v_add_u32_e32 v0, s7, v182
	v_ashrrev_i32_e32 v1, 31, v0
	v_lshlrev_b64 v[0:1], 5, v[0:1]
	v_lshl_add_u64 v[0:1], s[54:55], 0, v[0:1]
	global_load_dwordx4 v[20:23], v[0:1], off
	global_load_dwordx4 v[4:7], v[0:1], off offset:16
	v_add_u32_e32 v0, s7, v183
	v_ashrrev_i32_e32 v1, 31, v0
	v_lshlrev_b64 v[0:1], 5, v[0:1]
	v_lshl_add_u64 v[0:1], s[54:55], 0, v[0:1]
	global_load_dwordx4 v[16:19], v[0:1], off
	s_nop 0
	global_load_dwordx4 v[0:3], v[0:1], off offset:16
	s_and_saveexec_b64 s[0:1], s[36:37]
	ds_write_b32 v185, v65
	s_or_b64 exec, exec, s[0:1]
	s_waitcnt vmcnt(0) lgkmcnt(0)
	s_barrier
	s_and_saveexec_b64 s[0:1], s[38:39]
	v_mov_b32_e32 v32, s21
	v_mov_b32_e32 v33, -1
	ds_write_b32 v32, v33
	s_or_b64 exec, exec, s[0:1]
	v_add_u32_e32 v34, s6, v186
	v_mov_b64_e32 v[32:33], s[52:53]
	v_mad_i64_i32 v[32:33], s[0:1], v34, s4, v[32:33]
	v_lshl_add_u64 v[32:33], v[32:33], 0, v[64:65]
	s_mov_b64 s[0:1], 0x1000
	s_sub_i32 s9, s2, s59
	v_lshl_add_u64 v[138:139], v[32:33], 0, s[0:1]
	s_lshl_b32 s0, s9, 6
	v_mad_i64_i32 v[32:33], s[6:7], s0, v211, v[138:139]
	global_load_dwordx4 v[32:35], v[32:33], off
	s_sub_i32 s1, s62, s60
	s_sub_i32 s2, s5, s9
	s_min_i32 s35, s2, s1
	s_cmp_lt_i32 s35, 1
	s_waitcnt vmcnt(0) lgkmcnt(0)
	ds_write_b128 v187, v[32:35]
	s_waitcnt lgkmcnt(0)
	s_barrier
	s_cbranch_scc1 .LBB0_1067
	v_add_u32_e32 v223, s3, v174
	v_add_u32_e32 v224, s3, v175
	v_add_u32_e32 v225, s3, v182
	v_add_u32_e32 v226, s3, v183
	s_lshl_b32 s1, s59, 6
	s_lshl_b32 s2, s60, 6
	s_lshl_b32 s3, s18, 6
	s_add_i32 s63, s35, s9
	v_pk_mul_f32 v[140:141], v[30:31], 0.5 op_sel_hi:[1,0]
	v_pk_mul_f32 v[142:143], v[28:29], 0.5 op_sel_hi:[1,0]
	v_pk_mul_f32 v[144:145], v[14:15], 0.5 op_sel_hi:[1,0]
	v_pk_mul_f32 v[146:147], v[12:13], 0.5 op_sel_hi:[1,0]
	v_pk_mul_f32 v[148:149], v[26:27], 0.5 op_sel_hi:[1,0]
	v_pk_mul_f32 v[150:151], v[24:25], 0.5 op_sel_hi:[1,0]
	v_pk_mul_f32 v[152:153], v[10:11], 0.5 op_sel_hi:[1,0]
	v_pk_mul_f32 v[154:155], v[8:9], 0.5 op_sel_hi:[1,0]
	v_pk_mul_f32 v[156:157], v[22:23], 0.5 op_sel_hi:[1,0]
	v_pk_mul_f32 v[158:159], v[20:21], 0.5 op_sel_hi:[1,0]
	v_pk_mul_f32 v[160:161], v[6:7], 0.5 op_sel_hi:[1,0]
	v_pk_mul_f32 v[162:163], v[4:5], 0.5 op_sel_hi:[1,0]
	v_pk_mul_f32 v[164:165], v[18:19], 0.5 op_sel_hi:[1,0]
	v_pk_mul_f32 v[166:167], v[16:17], 0.5 op_sel_hi:[1,0]
	v_pk_mul_f32 v[168:169], v[2:3], 0.5 op_sel_hi:[1,0]
	v_pk_mul_f32 v[170:171], v[0:1], 0.5 op_sel_hi:[1,0]
	v_subrev_u32_e32 v227, s1, v172
	s_sub_i32 s66, s2, s3
	v_subrev_u32_e32 v228, s0, v216
	s_sub_i32 s67, 64, s1
	s_mov_b32 s70, 0
	s_mov_b32 s71, 0
	s_mov_b32 s72, 0
	s_mov_b32 s73, 0
	v_mov_b32_e32 v231, v184
	v_mov_b32_e32 v229, v184
	v_mov_b32_e32 v230, v184
	v_mov_b32_e32 v232, v184
	v_mov_b32_e32 v233, v184
	v_mov_b32_e32 v234, v184
	v_mov_b32_e32 v235, v184
	v_mov_b32_e32 v236, v184
	s_mov_b32 s74, 0
	s_mov_b32 s75, 0
	s_mov_b32 s76, 0
	s_mov_b32 s77, 0
	s_mov_b32 s78, 0
	s_mov_b32 s61, 0
	s_mov_b32 s16, 0
	s_mov_b32 s15, 0
	s_mov_b32 s8, 0
	s_mov_b32 s14, 0
	s_mov_b32 s13, 0
	s_mov_b32 s5, 0
	s_mov_b32 s68, 0
	v_lshrrev_b32_e32 v243, 5, v66
	v_lshlrev_b32_e32 v243, 12, v243
	s_add_i32 s0, s33, 0x0
	v_add_u32_e32 v248, s0, v243
	v_mov_b32_e32 v238, v248
	s_add_i32 s0, s33, 0x800
	v_add_u32_e32 v249, s0, v243
	v_mov_b32_e32 v239, v249
	s_add_i32 s0, s33, 0x2000
	v_add_u32_e32 v250, s0, v243
	v_mov_b32_e32 v240, v250
	s_add_i32 s0, s33, 0x2800
	v_add_u32_e32 v237, s0, v243
	v_mov_b32_e32 v241, v237
	v_cndmask_b32_e64 v242, 0, -1, s[40:41]
	v_cndmask_b32_e64 v188, v230, v231, s[40:41]
	v_cndmask_b32_e64 v189, v232, v229, s[40:41]
	v_cndmask_b32_e64 v190, v235, v233, s[40:41]
	v_cndmask_b32_e64 v191, v236, v234, s[40:41]

.LBB0_579:
	s_mul_i32 s0, s68, 0x2400
	v_add_u32_e32 v8, s0, v199
	ds_read_b128 v[0:3], v8
	ds_read_b128 v[4:7], v8 offset:32
	s_cmp_lt_i32 s9, s17
	s_cselect_b64 s[50:51], -1, 0
	v_cndmask_b32_e64 v176, v223, v212, s[50:51]
	s_waitcnt lgkmcnt(0)
	v_mfma_f32_32x32x16_bf16 v[48:63], v[72:75], v[0:3], 0
	v_add_u32_e32 v177, s66, v227
	v_add_u32_e32 v180, 32, v228
	v_mfma_f32_32x32x16_bf16 v[32:47], v[88:91], v[0:3], 0
	v_mfma_f32_32x32x16_bf16 v[48:63], v[76:79], v[4:7], v[48:63]
	v_mfma_f32_32x32x16_bf16 v[32:47], v[92:95], v[4:7], v[32:47]
	ds_read_b128 v[0:3], v8 offset:64
	ds_read_b128 v[4:7], v8 offset:96
	ds_read_b128 v[112:115], v8 offset:4672
	ds_read_b128 v[108:111], v8 offset:4704
	s_waitcnt lgkmcnt(0)
	v_mfma_f32_32x32x16_bf16 v[48:63], v[80:83], v[0:3], v[48:63]
	v_mfma_f32_32x32x16_bf16 v[48:63], v[84:87], v[4:7], v[48:63]
	v_mfma_f32_32x32x16_bf16 v[32:47], v[96:99], v[0:3], v[32:47]
	ds_read_b128 v[116:119], v8 offset:4640
	ds_read_b128 v[0:3], v8 offset:4608
	s_nop 8
	v_add_f32_e64 v8, v48, |v48|
	v_fma_f32 v48, v142, v8, 0
	v_add_f32_e64 v8, v49, |v49|
	v_fmac_f32_e32 v48, v143, v8
	v_add_f32_e64 v8, v50, |v50|
	v_fmac_f32_e32 v48, v140, v8
	v_mfma_f32_32x32x16_bf16 v[32:47], v[100:103], v[4:7], v[32:47]
	v_add_f32_e64 v4, v51, |v51|
	v_fmac_f32_e32 v48, v141, v4
	v_add_f32_e64 v4, v52, |v52|
	v_fmac_f32_e32 v48, v146, v4
	v_add_f32_e64 v4, v53, |v53|
	v_fmac_f32_e32 v48, v147, v4
	v_add_f32_e64 v4, v54, |v54|
	v_fmac_f32_e32 v48, v144, v4
	v_add_f32_e64 v4, v55, |v55|
	s_waitcnt lgkmcnt(0)
	v_mfma_f32_32x32x16_bf16 v[16:31], v[72:75], v[0:3], 0
	v_fmac_f32_e32 v48, v145, v4
	v_mfma_f32_32x32x16_bf16 v[0:15], v[88:91], v[0:3], 0
	v_cmp_le_i32_e32 vcc, v177, v176
	v_ashrrev_i32_e32 v247, 31, v48
	v_bitop3_b32 v244, v247, v48, s93 bitop3:0x36
	v_cndmask_b32_e32 v246, v214, v48, vcc
	v_cmpx_ge_f32_e32 vcc, v246, v188
	v_and_or_b32 v244, v244, s80, v180
	s_nop 0
	v_and_b32_e32 v247, vcc_lo, v242
	v_mbcnt_lo_u32_b32 v243, v247, 0
	v_mbcnt_hi_u32_b32 v243, vcc_hi, v243
	v_lshl_add_u32 v245, v243, 2, v238
	ds_write_b32 v245, v244
	s_mov_b64 exec, -1
	v_bcnt_u32_b32 v246, vcc_lo, 0
	v_bcnt_u32_b32 v247, vcc_hi, 0
	v_cndmask_b32_e64 v246, v247, v246, s[40:41]
	v_lshl_add_u32 v238, v246, 2, v238
	v_add_f32_e64 v50, v56, |v56|
	v_fma_f32 v50, v150, v50, 0
	v_add_f32_e64 v51, v57, |v57|
	v_fmac_f32_e32 v50, v151, v51
	v_add_f32_e64 v51, v58, |v58|
	v_fmac_f32_e32 v50, v148, v51
	v_add_f32_e64 v51, v59, |v59|
	v_mfma_f32_32x32x16_bf16 v[16:31], v[76:79], v[116:119], v[16:31]
	v_fmac_f32_e32 v50, v149, v51
	v_add_f32_e64 v51, v60, |v60|
	v_fmac_f32_e32 v50, v154, v51
	v_add_f32_e64 v51, v61, |v61|
	v_fmac_f32_e32 v50, v155, v51
	v_add_f32_e64 v51, v62, |v62|
	v_fmac_f32_e32 v50, v152, v51
	v_mfma_f32_32x32x16_bf16 v[0:15], v[92:95], v[116:119], v[0:15]
	v_add_f32_e64 v51, v63, |v63|
	v_cndmask_b32_e64 v48, v224, v212, s[50:51]
	v_fmac_f32_e32 v50, v153, v51
	v_cmp_le_i32_e32 vcc, v177, v48
	v_ashrrev_i32_e32 v247, 31, v50
	v_bitop3_b32 v244, v247, v50, s93 bitop3:0x36
	v_cndmask_b32_e32 v246, v214, v50, vcc
	v_cmpx_ge_f32_e32 vcc, v246, v189
	v_and_or_b32 v244, v244, s80, v180
	s_nop 0
	v_and_b32_e32 v247, vcc_lo, v242
	v_mbcnt_lo_u32_b32 v243, v247, 0
	v_mbcnt_hi_u32_b32 v243, vcc_hi, v243
	v_lshl_add_u32 v245, v243, 2, v239
	ds_write_b32 v245, v244
	s_mov_b64 exec, -1
	v_bcnt_u32_b32 v246, vcc_lo, 0
	v_bcnt_u32_b32 v247, vcc_hi, 0
	v_cndmask_b32_e64 v246, v247, v246, s[40:41]
	v_lshl_add_u32 v239, v246, 2, v239
	v_add_f32_e64 v32, v32, |v32|
	v_fma_f32 v32, v158, v32, 0
	v_add_f32_e64 v33, v33, |v33|
	v_fmac_f32_e32 v32, v159, v33
	v_add_f32_e64 v33, v34, |v34|
	v_fmac_f32_e32 v32, v156, v33
	v_add_f32_e64 v33, v35, |v35|
	v_mfma_f32_32x32x16_bf16 v[16:31], v[80:83], v[112:115], v[16:31]
	v_fmac_f32_e32 v32, v157, v33
	v_add_f32_e64 v33, v36, |v36|
	v_fmac_f32_e32 v32, v162, v33
	v_add_f32_e64 v33, v37, |v37|
	v_fmac_f32_e32 v32, v163, v33
	v_add_f32_e64 v33, v38, |v38|
	v_fmac_f32_e32 v32, v160, v33
	v_mfma_f32_32x32x16_bf16 v[0:15], v[96:99], v[112:115], v[0:15]
	v_add_f32_e64 v33, v39, |v39|
	v_cndmask_b32_e64 v50, v225, v212, s[50:51]
	v_fmac_f32_e32 v32, v161, v33
	v_cmp_le_i32_e32 vcc, v177, v50
	v_ashrrev_i32_e32 v247, 31, v32
	v_bitop3_b32 v244, v247, v32, s93 bitop3:0x36
	v_cndmask_b32_e32 v246, v214, v32, vcc
	v_cmpx_ge_f32_e32 vcc, v246, v190
	v_and_or_b32 v244, v244, s80, v180
	s_nop 0
	v_and_b32_e32 v247, vcc_lo, v242
	v_mbcnt_lo_u32_b32 v243, v247, 0
	v_mbcnt_hi_u32_b32 v243, vcc_hi, v243
	v_lshl_add_u32 v245, v243, 2, v240
	ds_write_b32 v245, v244
	s_mov_b64 exec, -1
	v_bcnt_u32_b32 v246, vcc_lo, 0
	v_bcnt_u32_b32 v247, vcc_hi, 0
	v_cndmask_b32_e64 v246, v247, v246, s[40:41]
	v_lshl_add_u32 v240, v246, 2, v240
	v_add_f32_e64 v34, v40, |v40|
	v_fma_f32 v35, v166, v34, 0
	v_add_f32_e64 v34, v41, |v41|
	v_fmac_f32_e32 v35, v167, v34
	v_add_f32_e64 v34, v42, |v42|
	v_fmac_f32_e32 v35, v164, v34
	v_add_f32_e64 v34, v43, |v43|
	v_mfma_f32_32x32x16_bf16 v[16:31], v[84:87], v[108:111], v[16:31]
	v_fmac_f32_e32 v35, v165, v34
	v_add_f32_e64 v34, v44, |v44|
	v_fmac_f32_e32 v35, v170, v34
	v_add_f32_e64 v34, v45, |v45|
	v_fmac_f32_e32 v35, v171, v34
	v_add_f32_e64 v34, v46, |v46|
	v_fmac_f32_e32 v35, v168, v34
	v_mfma_f32_32x32x16_bf16 v[0:15], v[100:103], v[108:111], v[0:15]
	v_add_f32_e64 v34, v47, |v47|
	v_cndmask_b32_e64 v32, v226, v212, s[50:51]
	v_fmac_f32_e32 v35, v169, v34
	v_cmp_le_i32_e32 vcc, v177, v32
	v_ashrrev_i32_e32 v247, 31, v35
	v_bitop3_b32 v244, v247, v35, s93 bitop3:0x36
	v_cndmask_b32_e32 v246, v214, v35, vcc
	v_cmpx_ge_f32_e32 vcc, v246, v191
	v_and_or_b32 v244, v244, s80, v180
	s_nop 0
	v_and_b32_e32 v247, vcc_lo, v242
	v_mbcnt_lo_u32_b32 v243, v247, 0
	v_mbcnt_hi_u32_b32 v243, vcc_hi, v243
	v_lshl_add_u32 v245, v243, 2, v241
	ds_write_b32 v245, v244
	s_mov_b64 exec, -1
	v_bcnt_u32_b32 v246, vcc_lo, 0
	v_bcnt_u32_b32 v247, vcc_hi, 0
	v_cndmask_b32_e64 v246, v247, v246, s[40:41]
	v_lshl_add_u32 v241, v246, 2, v241
	v_add_f32_e64 v16, v16, |v16|
	v_fma_f32 v16, v142, v16, 0
	v_add_f32_e64 v17, v17, |v17|
	v_fmac_f32_e32 v16, v143, v17
	v_add_f32_e64 v17, v18, |v18|
	v_fmac_f32_e32 v16, v140, v17
	v_add_f32_e64 v17, v19, |v19|
	v_fmac_f32_e32 v16, v141, v17
	v_add_f32_e64 v17, v20, |v20|
	v_fmac_f32_e32 v16, v146, v17
	v_add_f32_e64 v17, v21, |v21|
	v_fmac_f32_e32 v16, v147, v17
	v_add_f32_e64 v17, v22, |v22|
	v_fmac_f32_e32 v16, v144, v17
	v_add_f32_e64 v17, v23, |v23|
	v_add_u32_e32 v35, 32, v177
	v_fmac_f32_e32 v16, v145, v17
	v_cmp_le_i32_e32 vcc, v35, v176
	v_ashrrev_i32_e32 v247, 31, v16
	v_bitop3_b32 v244, v247, v16, s93 bitop3:0x36
	v_cndmask_b32_e32 v246, v214, v16, vcc
	v_cmpx_ge_f32_e32 vcc, v246, v188
	v_and_or_b32 v244, v244, s80, v228
	s_nop 0
	v_and_b32_e32 v247, vcc_lo, v242
	v_mbcnt_lo_u32_b32 v243, v247, 0
	v_mbcnt_hi_u32_b32 v243, vcc_hi, v243
	v_lshl_add_u32 v245, v243, 2, v238
	ds_write_b32 v245, v244
	s_mov_b64 exec, -1
	v_bcnt_u32_b32 v246, vcc_lo, 0
	v_bcnt_u32_b32 v247, vcc_hi, 0
	v_cndmask_b32_e64 v246, v247, v246, s[40:41]
	v_lshl_add_u32 v238, v246, 2, v238
	v_add_f32_e64 v16, v24, |v24|
	v_fma_f32 v16, v150, v16, 0
	v_add_f32_e64 v17, v25, |v25|
	v_fmac_f32_e32 v16, v151, v17
	v_add_f32_e64 v17, v26, |v26|
	v_fmac_f32_e32 v16, v148, v17
	v_add_f32_e64 v17, v27, |v27|
	v_fmac_f32_e32 v16, v149, v17
	v_add_f32_e64 v17, v28, |v28|
	v_fmac_f32_e32 v16, v154, v17
	v_add_f32_e64 v17, v29, |v29|
	v_fmac_f32_e32 v16, v155, v17
	v_add_f32_e64 v17, v30, |v30|
	v_fmac_f32_e32 v16, v152, v17
	v_add_f32_e64 v17, v31, |v31|
	v_fmac_f32_e32 v16, v153, v17
	v_cmp_le_i32_e32 vcc, v35, v48
	v_ashrrev_i32_e32 v247, 31, v16
	v_bitop3_b32 v244, v247, v16, s93 bitop3:0x36
	v_cndmask_b32_e32 v246, v214, v16, vcc
	v_cmpx_ge_f32_e32 vcc, v246, v189
	v_and_or_b32 v244, v244, s80, v228
	s_nop 0
	v_and_b32_e32 v247, vcc_lo, v242
	v_mbcnt_lo_u32_b32 v243, v247, 0
	v_mbcnt_hi_u32_b32 v243, vcc_hi, v243
	v_lshl_add_u32 v245, v243, 2, v239
	ds_write_b32 v245, v244
	s_mov_b64 exec, -1
	v_bcnt_u32_b32 v246, vcc_lo, 0
	v_bcnt_u32_b32 v247, vcc_hi, 0
	v_cndmask_b32_e64 v246, v247, v246, s[40:41]
	v_lshl_add_u32 v239, v246, 2, v239
	v_add_f32_e64 v0, v0, |v0|
	v_fma_f32 v0, v158, v0, 0
	v_add_f32_e64 v1, v1, |v1|
	v_fmac_f32_e32 v0, v159, v1
	v_add_f32_e64 v1, v2, |v2|
	v_fmac_f32_e32 v0, v156, v1
	v_add_f32_e64 v1, v3, |v3|
	v_fmac_f32_e32 v0, v157, v1
	v_add_f32_e64 v1, v4, |v4|
	v_fmac_f32_e32 v0, v162, v1
	v_add_f32_e64 v1, v5, |v5|
	v_fmac_f32_e32 v0, v163, v1
	v_add_f32_e64 v1, v6, |v6|
	v_fmac_f32_e32 v0, v160, v1
	v_add_f32_e64 v1, v7, |v7|
	v_fmac_f32_e32 v0, v161, v1
	v_cmp_le_i32_e32 vcc, v35, v50
	v_ashrrev_i32_e32 v247, 31, v0
	v_bitop3_b32 v244, v247, v0, s93 bitop3:0x36
	v_cndmask_b32_e32 v246, v214, v0, vcc
	v_cmpx_ge_f32_e32 vcc, v246, v190
	v_and_or_b32 v244, v244, s80, v228
	s_nop 0
	v_and_b32_e32 v247, vcc_lo, v242
	v_mbcnt_lo_u32_b32 v243, v247, 0
	v_mbcnt_hi_u32_b32 v243, vcc_hi, v243
	v_lshl_add_u32 v245, v243, 2, v240
	ds_write_b32 v245, v244
	s_mov_b64 exec, -1
	v_bcnt_u32_b32 v246, vcc_lo, 0
	v_bcnt_u32_b32 v247, vcc_hi, 0
	v_cndmask_b32_e64 v246, v247, v246, s[40:41]
	v_lshl_add_u32 v240, v246, 2, v240
	v_add_f32_e64 v0, v8, |v8|
	v_fma_f32 v0, v166, v0, 0
	v_add_f32_e64 v1, v9, |v9|
	v_fmac_f32_e32 v0, v167, v1
	v_add_f32_e64 v1, v10, |v10|
	v_fmac_f32_e32 v0, v164, v1
	v_add_f32_e64 v1, v11, |v11|
	v_fmac_f32_e32 v0, v165, v1
	v_add_f32_e64 v1, v12, |v12|
	v_fmac_f32_e32 v0, v170, v1
	v_add_f32_e64 v1, v13, |v13|
	v_fmac_f32_e32 v0, v171, v1
	v_add_f32_e64 v1, v14, |v14|
	v_fmac_f32_e32 v0, v168, v1
	v_add_f32_e64 v1, v15, |v15|
	v_fmac_f32_e32 v0, v169, v1
	v_cmp_le_i32_e32 vcc, v35, v32
	v_ashrrev_i32_e32 v247, 31, v0
	v_bitop3_b32 v244, v247, v0, s93 bitop3:0x36
	v_cndmask_b32_e32 v246, v214, v0, vcc
	v_cmpx_ge_f32_e32 vcc, v246, v191
	v_and_or_b32 v244, v244, s80, v228
	s_nop 0
	v_and_b32_e32 v247, vcc_lo, v242
	v_mbcnt_lo_u32_b32 v243, v247, 0
	v_mbcnt_hi_u32_b32 v243, vcc_hi, v243
	v_lshl_add_u32 v245, v243, 2, v241
	ds_write_b32 v245, v244
	s_mov_b64 exec, -1
	v_bcnt_u32_b32 v246, vcc_lo, 0
	v_bcnt_u32_b32 v247, vcc_hi, 0
	v_cndmask_b32_e64 v246, v247, v246, s[40:41]
	v_lshl_add_u32 v241, v246, 2, v241
	v_sub_u32_e32 v243, v238, v248
	v_sub_u32_e32 v244, v239, v249
	v_sub_u32_e32 v245, v240, v250
	v_sub_u32_e32 v246, v241, v237
	v_max3_u32 v243, v243, v244, v245
	v_max_u32_e32 v243, v243, v246
	v_mov_b32_e32 v244, s21
	v_mov_b32_e32 v246, s9
	v_cmpx_lt_u32_e32 vcc, 0x700, v243
	v_cmpx_eq_u32_e32 vcc, 0, v172
	ds_write_b32 v244, v246
	s_mov_b64 exec, -1
	s_andn2_b64 vcc, exec, s[2:3]
	s_xor_b32 s68, s68, 1
	s_cbranch_vccnz .Lto_nost
	s_mul_i32 s2, s68, 0x2400
	v_add_u32_e32 v0, s2, v187
	s_waitcnt vmcnt(0)
	ds_write_b128 v0, v[104:107]
.Lto_nost:
	v_mov_b32_e32 v0, s21
	s_waitcnt lgkmcnt(0)
	s_barrier
	ds_read_b32 v0, v0
	s_waitcnt lgkmcnt(0)
	v_cmp_ne_u32_e32 vcc, s9, v0
	s_and_b64 vcc, exec, vcc
	s_cbranch_vccnz .LBB0_1045
	s_nop 0
	v_readlane_b32 s0, v238, 0
	v_readlane_b32 s1, v238, 32
	s_sub_u32 s0, s0, s33
	s_sub_u32 s0, s0, 0x0
	s_lshr_b32 s78, s0, 2
	s_sub_u32 s1, s1, s33
	s_sub_u32 s1, s1, 0x1000
	s_lshr_b32 s16, s1, 2
	v_readlane_b32 s0, v239, 0
	v_readlane_b32 s1, v239, 32
	s_sub_u32 s0, s0, s33
	s_sub_u32 s0, s0, 0x800
	s_lshr_b32 s61, s0, 2
	s_sub_u32 s1, s1, s33
	s_sub_u32 s1, s1, 0x1800
	s_lshr_b32 s15, s1, 2
	v_readlane_b32 s0, v240, 0
	v_readlane_b32 s1, v240, 32
	s_sub_u32 s0, s0, s33
	s_sub_u32 s0, s0, 0x2000
	s_lshr_b32 s8, s0, 2
	s_sub_u32 s1, s1, s33
	s_sub_u32 s1, s1, 0x3000
	s_lshr_b32 s13, s1, 2
	v_readlane_b32 s0, v241, 0
	v_readlane_b32 s1, v241, 32
	s_sub_u32 s0, s0, s33
	s_sub_u32 s0, s0, 0x2800
	s_lshr_b32 s14, s0, 2
	s_sub_u32 s1, s1, s33
	s_sub_u32 s1, s1, 0x3800
	s_lshr_b32 s5, s1, 2
	v_and_b32_e32 v58, 15, v66
	v_lshlrev_b32_e32 v41, 4, v58
	v_sub_u32_e32 v40, v195, v41
	v_lshrrev_b32_e32 v57, 4, v66
	v_lshl_add_u32 v59, v57, 11, s33
	v_add_u32_e32 v60, v59, v41
	s_mov_b32 s22, 0
	s_mov_b32 s23, 0
	s_cmpk_gt_i32 s78, 0x140
	s_cselect_b32 s0, 0xffff, 0
	s_or_b32 s22, s22, s0
	s_cmpk_gt_i32 s61, 0x140
	s_cselect_b32 s0, 0xffff0000, 0
	s_or_b32 s22, s22, s0
	s_cmpk_gt_i32 s16, 0x140
	s_cselect_b32 s0, 0xffff, 0
	s_or_b32 s23, s23, s0
	s_cmpk_gt_i32 s15, 0x140
	s_cselect_b32 s0, 0xffff0000, 0
	s_or_b32 s23, s23, s0
	s_cmp_eq_u64 s[22:23], 0
	s_cbranch_scc1 .Lp2apr0_end
	v_mov_b32_e32 v32, s78
	v_mov_b32_e32 v41, s61
	v_mov_b32_e32 v42, s16
	v_mov_b32_e32 v43, s15
	s_nop 0
	v_mov_b32_dpp v32, v41 quad_perm:[0,1,2,3] row_mask:0x2 bank_mask:0xf
	v_mov_b32_dpp v32, v42 quad_perm:[0,1,2,3] row_mask:0x4 bank_mask:0xf
	v_mov_b32_dpp v32, v43 quad_perm:[0,1,2,3] row_mask:0x8 bank_mask:0xf
	v_mov_b32_e32 v33, s73
	v_mov_b32_e32 v41, s72
	v_mov_b32_e32 v42, s71
	v_mov_b32_e32 v43, s70
	s_nop 0
	v_mov_b32_dpp v33, v41 quad_perm:[0,1,2,3] row_mask:0x2 bank_mask:0xf
	v_mov_b32_dpp v33, v42 quad_perm:[0,1,2,3] row_mask:0x4 bank_mask:0xf
	v_mov_b32_dpp v33, v43 quad_perm:[0,1,2,3] row_mask:0x8 bank_mask:0xf
	ds_read_b128 v[0:3], v60
	ds_read_b128 v[4:7], v60 offset:256
	ds_read_b128 v[8:11], v60 offset:512
	ds_read_b128 v[12:15], v60 offset:768
	ds_read_b128 v[16:19], v60 offset:1024
	ds_read_b128 v[20:23], v60 offset:1280
	ds_read_b128 v[24:27], v60 offset:1536
	ds_read_b128 v[28:31], v60 offset:1792
	v_lshlrev_b32_e32 v41, 2, v58
	v_sub_u32_e32 v41, v32, v41
	s_waitcnt lgkmcnt(0)
	v_mov_b32_e32 v47, 20
	v_subrev_u32_e32 v42, 320, v41
	v_med3_i32 v43, v42, 0, 4
	v_add_u32_e32 v47, v47, v43
	v_cmp_lt_i32_e32 vcc, 0, v42
	v_cmp_lt_i32_e64 s[0:1], 1, v42
	v_cmp_lt_i32_e64 s[2:3], 2, v42
	v_cndmask_b32_e32 v20, 0, v20, vcc
	v_cmp_lt_i32_e32 vcc, 3, v42
	v_cndmask_b32_e64 v21, 0, v21, s[0:1]
	v_cndmask_b32_e64 v22, 0, v22, s[2:3]
	v_cndmask_b32_e32 v23, 0, v23, vcc
	v_subrev_u32_e32 v42, 384, v41
	v_med3_i32 v43, v42, 0, 4
	v_add_u32_e32 v47, v47, v43
	v_cmp_lt_i32_e32 vcc, 0, v42
	v_cmp_lt_i32_e64 s[0:1], 1, v42
	v_cmp_lt_i32_e64 s[2:3], 2, v42
	v_cndmask_b32_e32 v24, 0, v24, vcc
	v_cmp_lt_i32_e32 vcc, 3, v42
	v_cndmask_b32_e64 v25, 0, v25, s[0:1]
	v_cndmask_b32_e64 v26, 0, v26, s[2:3]
	v_cndmask_b32_e32 v27, 0, v27, vcc
	v_subrev_u32_e32 v42, 448, v41
	v_med3_i32 v43, v42, 0, 4
	v_add_u32_e32 v47, v47, v43
	v_cmp_lt_i32_e32 vcc, 0, v42
	v_cmp_lt_i32_e64 s[0:1], 1, v42
	v_cmp_lt_i32_e64 s[2:3], 2, v42
	v_cndmask_b32_e32 v28, 0, v28, vcc
	v_cmp_lt_i32_e32 vcc, 3, v42
	v_cndmask_b32_e64 v29, 0, v29, s[0:1]
	v_cndmask_b32_e64 v30, 0, v30, s[2:3]
	v_cndmask_b32_e32 v31, 0, v31, vcc
	v_max3_u32 v35, v0, v1, v2
	v_max3_u32 v35, v3, v4, v35
	v_max3_u32 v35, v5, v6, v35
	v_max3_u32 v35, v7, v8, v35
	v_max3_u32 v35, v9, v10, v35
	v_max3_u32 v35, v11, v12, v35
	v_max3_u32 v35, v13, v14, v35
	v_max3_u32 v35, v15, v16, v35
	v_max3_u32 v35, v17, v18, v35
	v_max3_u32 v35, v19, v20, v35
	v_max3_u32 v35, v21, v22, v35
	v_max3_u32 v35, v23, v24, v35
	v_max3_u32 v35, v25, v26, v35
	v_max3_u32 v35, v27, v28, v35
	v_max3_u32 v35, v29, v30, v35
	v_max_u32_e32 v35, v31, v35
	s_nop 1
	v_max_u32_dpp v35, v35, v35 row_ror:1 row_mask:0xf bank_mask:0xf
	s_nop 1
	v_max_u32_dpp v35, v35, v35 row_ror:2 row_mask:0xf bank_mask:0xf
	s_nop 1
	v_max_u32_dpp v35, v35, v35 row_ror:4 row_mask:0xf bank_mask:0xf
	s_nop 1
	v_max_u32_dpp v35, v35, v35 row_ror:8 row_mask:0xf bank_mask:0xf
	v_and_b32_e32 v34, 0xffffe000, v33
	v_cmp_eq_u32_e32 vcc, 0, v33
	s_and_b64 vcc, vcc, s[22:23]
	s_cbranch_vccz .Lp2apr0_nomin
	v_add_u32_e32 v41, -1, v0
	v_add_u32_e32 v42, -1, v1
	v_min_u32_e32 v43, v41, v42
	v_add_u32_e32 v41, -1, v2
	v_add_u32_e32 v42, -1, v3
	v_min3_u32 v43, v41, v42, v43
	v_add_u32_e32 v41, -1, v4
	v_add_u32_e32 v42, -1, v5
	v_min3_u32 v43, v41, v42, v43
	v_add_u32_e32 v41, -1, v6
	v_add_u32_e32 v42, -1, v7
	v_min3_u32 v43, v41, v42, v43
	v_add_u32_e32 v41, -1, v8
	v_add_u32_e32 v42, -1, v9
	v_min3_u32 v43, v41, v42, v43
	v_add_u32_e32 v41, -1, v10
	v_add_u32_e32 v42, -1, v11
	v_min3_u32 v43, v41, v42, v43
	v_add_u32_e32 v41, -1, v12
	v_add_u32_e32 v42, -1, v13
	v_min3_u32 v43, v41, v42, v43
	v_add_u32_e32 v41, -1, v14
	v_add_u32_e32 v42, -1, v15
	v_min3_u32 v43, v41, v42, v43
	v_add_u32_e32 v41, -1, v16
	v_add_u32_e32 v42, -1, v17
	v_min3_u32 v43, v41, v42, v43
	v_add_u32_e32 v41, -1, v18
	v_add_u32_e32 v42, -1, v19
	v_min3_u32 v43, v41, v42, v43
	v_add_u32_e32 v41, -1, v20
	v_add_u32_e32 v42, -1, v21
	v_min3_u32 v43, v41, v42, v43
	v_add_u32_e32 v41, -1, v22
	v_add_u32_e32 v42, -1, v23
	v_min3_u32 v43, v41, v42, v43
	v_add_u32_e32 v41, -1, v24
	v_add_u32_e32 v42, -1, v25
	v_min3_u32 v43, v41, v42, v43
	v_add_u32_e32 v41, -1, v26
	v_add_u32_e32 v42, -1, v27
	v_min3_u32 v43, v41, v42, v43
	v_add_u32_e32 v41, -1, v28
	v_add_u32_e32 v42, -1, v29
	v_min3_u32 v43, v41, v42, v43
	v_add_u32_e32 v41, -1, v30
	v_add_u32_e32 v42, -1, v31
	v_min3_u32 v43, v41, v42, v43
	s_nop 1
	v_min_u32_dpp v43, v43, v43 row_ror:1 row_mask:0xf bank_mask:0xf
	s_nop 1
	v_min_u32_dpp v43, v43, v43 row_ror:2 row_mask:0xf bank_mask:0xf
	s_nop 1
	v_min_u32_dpp v43, v43, v43 row_ror:4 row_mask:0xf bank_mask:0xf
	s_nop 1
	v_min_u32_dpp v43, v43, v43 row_ror:8 row_mask:0xf bank_mask:0xf
	v_add_u32_e32 v43, 1, v43
	v_cmp_eq_u32_e32 vcc, 0, v33
	s_nop 1
	v_cndmask_b32_e32 v34, v34, v43, vcc

.Lp2apr1_o3:
.Lp2apr1_end:
	s_lshl_b32 s0, s78, 2
	s_add_u32 s0, s0, s33
	s_add_u32 s0, s0, 0x0
	s_lshl_b32 s1, s16, 2
	s_add_u32 s1, s1, s33
	s_add_u32 s1, s1, 0x1000
	v_mov_b32_e32 v238, s1
	v_mov_b32_e32 v243, s0
	v_cndmask_b32_e64 v238, v238, v243, s[40:41]
	s_lshl_b32 s0, s61, 2
	s_add_u32 s0, s0, s33
	s_add_u32 s0, s0, 0x800
	s_lshl_b32 s1, s15, 2
	s_add_u32 s1, s1, s33
	s_add_u32 s1, s1, 0x1800
	v_mov_b32_e32 v239, s1
	v_mov_b32_e32 v243, s0
	v_cndmask_b32_e64 v239, v239, v243, s[40:41]
	s_lshl_b32 s0, s8, 2
	s_add_u32 s0, s0, s33
	s_add_u32 s0, s0, 0x2000
	s_lshl_b32 s1, s13, 2
	s_add_u32 s1, s1, s33
	s_add_u32 s1, s1, 0x3000
	v_mov_b32_e32 v240, s1
	v_mov_b32_e32 v243, s0
	v_cndmask_b32_e64 v240, v240, v243, s[40:41]
	s_lshl_b32 s0, s14, 2
	s_add_u32 s0, s0, s33
	s_add_u32 s0, s0, 0x2800
	s_lshl_b32 s1, s5, 2
	s_add_u32 s1, s1, s33
	s_add_u32 s1, s1, 0x3800
	v_mov_b32_e32 v241, s1
	v_mov_b32_e32 v243, s0
	v_cndmask_b32_e64 v241, v241, v243, s[40:41]
	v_cndmask_b32_e64 v188, v230, v231, s[40:41]
	v_cndmask_b32_e64 v189, v232, v229, s[40:41]
	v_cndmask_b32_e64 v190, v235, v233, s[40:41]
	v_cndmask_b32_e64 v191, v236, v234, s[40:41]

.LBB0_1066:
	v_add_u32_e32 v188, 0x40, v66
	v_add_u32_e32 v189, 0x80, v66
	v_add_u32_e32 v190, 0xc0, v66
	v_add_u32_e32 v191, 0x100, v66
	s_nop 0
	v_readlane_b32 s0, v238, 0
	v_readlane_b32 s1, v238, 32
	s_sub_u32 s0, s0, s33
	s_sub_u32 s0, s0, 0x0
	s_lshr_b32 s78, s0, 2
	s_sub_u32 s1, s1, s33
	s_sub_u32 s1, s1, 0x1000
	s_lshr_b32 s16, s1, 2
	v_readlane_b32 s0, v239, 0
	v_readlane_b32 s1, v239, 32
	s_sub_u32 s0, s0, s33
	s_sub_u32 s0, s0, 0x800
	s_lshr_b32 s61, s0, 2
	s_sub_u32 s1, s1, s33
	s_sub_u32 s1, s1, 0x1800
	s_lshr_b32 s15, s1, 2
	v_readlane_b32 s0, v240, 0
	v_readlane_b32 s1, v240, 32
	s_sub_u32 s0, s0, s33
	s_sub_u32 s0, s0, 0x2000
	s_lshr_b32 s8, s0, 2
	s_sub_u32 s1, s1, s33
	s_sub_u32 s1, s1, 0x3000
	s_lshr_b32 s13, s1, 2
	v_readlane_b32 s0, v241, 0
	v_readlane_b32 s1, v241, 32
	s_sub_u32 s0, s0, s33
	s_sub_u32 s0, s0, 0x2800
	s_lshr_b32 s14, s0, 2
	s_sub_u32 s1, s1, s33
	s_sub_u32 s1, s1, 0x3800
	s_lshr_b32 s5, s1, 2
	s_and_b32 s0, s73, 0xffffe000
	s_and_b32 s66, s72, 0xffffe000
	s_and_b32 s63, s71, 0xffffe000
	s_and_b32 s51, s70, 0xffffe000
	s_and_b32 s50, s74, 0xffffe000
	s_and_b32 s23, s75, 0xffffe000
	s_and_b32 s22, s76, 0xffffe000
	s_and_b32 s9, s77, 0xffffe000
	s_andn2_b64 vcc, exec, s[64:65]
	s_cbranch_vccnz .LBB0_567
	s_branch .LBB0_1068
